# grid barrier tail rewritten: leader wbl2 + non-returning TOP add, everyone polls TOP >= (gen+1)*nx, early invalidate
# speedup vs baseline: 1.0047x; 1.0045x over previous
; __device__ __forceinline__ unsigned xb_ld(unsigned* p)              { return __hip_atomic_load(p, __ATOMIC_RELAXED, __HIP_MEMORY_SCOPE_AGENT); }
; __device__ __forceinline__ unsigned xb_add(unsigned* p, unsigned v) { return __hip_atomic_fetch_add(p, v, __ATOMIC_RELAXED, __HIP_MEMORY_SCOPE_AGENT); }
; #define XB_SPIN(cond, bar) do { unsigned _sp = 0; while (cond) { __builtin_amdgcn_s_sleep(1); \
;     if ((++_sp & 255u) == 0u) { if (xb_ld(&(bar)[XB_TMO])) break; if (_sp > XB_SPIN_CAP) { atomicAdd(&(bar)[XB_TMO], 1u); break; } } } } while (0)
; __device__ __forceinline__ void xcd_barrier(const XcdBarrier& b) {
;     ...
;         unsigned nloc = b.st[0], nx = b.st[1];
;         if (nloc == 0u) { xcd_barrier_complete(bar, b.x, nloc, nx); b.st[0] = nloc; b.st[1] = nx; }
;         const unsigned old = xb_add(&bar[XB_XSUB(b.x)], 1u);
;         const unsigned gen = old / nloc;
;         if (old + 1u == (gen + 1u) * nloc) {
;             __builtin_amdgcn_fence(__ATOMIC_RELEASE, "agent");
;             asm volatile("s_waitcnt vmcnt(0)" ::: "memory");
;             const unsigned og = xb_add(&bar[XB_TOP], 1u);
;             const unsigned tg = og / nx;
;             if (og + 1u == (tg + 1u) * nx) xb_add(&bar[XB_TOPGEN], 1u);
;             else XB_SPIN(xb_ld(&bar[XB_TOPGEN]) == tg, bar);
;             __builtin_amdgcn_fence(__ATOMIC_ACQUIRE, "agent");
;             asm volatile("s_waitcnt vmcnt(0)" ::: "memory");
;         } else {
;             XB_SPIN(xb_ld(&bar[XB_TOPGEN]) == gen, bar);
.LBB0_93:
	s_lshl_b32 s3, s2, 8
	v_readlane_b32 s4, v252, 8
	v_readlane_b32 s5, v252, 9
	s_add_u32 s4, s4, s3
	s_addc_u32 s5, s5, 0
	v_mov_b32_e32 v2, 0x1000
	v_mov_b32_e32 v4, 1
	v_sub_u32_e32 v5, 0, v3
	global_atomic_add v4, v2, v4, s[4:5] offset:1024 sc0
	v_cvt_f32_u32_e32 v2, v3
	v_rcp_iflag_f32_e32 v2, v2
	s_nop 0
	v_mul_f32_e32 v2, 0x4f7ffffe, v2
	v_cvt_u32_f32_e32 v2, v2
	v_mul_lo_u32 v5, v5, v2
	v_mul_hi_u32 v5, v2, v5
	v_add_u32_e32 v2, v2, v5
	s_waitcnt vmcnt(0)
	v_mul_hi_u32 v2, v4, v2
	v_mul_lo_u32 v5, v2, v3
	v_sub_u32_e32 v5, v4, v5
	v_add_u32_e32 v6, 1, v2
	v_cmp_ge_u32_e32 vcc, v5, v3
	v_add_u32_e32 v4, 1, v4
	s_nop 0
	v_cndmask_b32_e32 v2, v2, v6, vcc
	v_sub_u32_e32 v6, v5, v3
	v_cndmask_b32_e32 v5, v5, v6, vcc
	v_add_u32_e32 v6, 1, v2
	v_cmp_ge_u32_e32 vcc, v5, v3
	s_nop 1
	v_cndmask_b32_e32 v2, v2, v6, vcc
	v_mul_lo_u32 v5, v3, v2
	v_add_u32_e32 v3, v5, v3
	v_cmp_ne_u32_e32 vcc, v4, v3
	s_waitcnt lgkmcnt(0)
	v_add_u32_e32 v5, 1, v2
	v_mul_lo_u32 v5, v5, v1
	v_readlane_b32 s98, v252, 8
	v_readlane_b32 s99, v252, 9
	v_mov_b32_e32 v7, 0x3400
	v_mov_b32_e32 v8, 1
	s_nop 4
	s_cbranch_vccnz .Lxb_p0_nl
	buffer_wbl2 sc1
	s_waitcnt vmcnt(0)
	global_atomic_add v7, v8, s[98:99]
	buffer_inv sc1
	s_branch .Lxb_p0_poll

; __device__ __forceinline__ unsigned xb_ld(unsigned* p)              { return __hip_atomic_load(p, __ATOMIC_RELAXED, __HIP_MEMORY_SCOPE_AGENT); }
; __device__ __forceinline__ unsigned xb_add(unsigned* p, unsigned v) { return __hip_atomic_fetch_add(p, v, __ATOMIC_RELAXED, __HIP_MEMORY_SCOPE_AGENT); }
; #define XB_SPIN(cond, bar) do { unsigned _sp = 0; while (cond) { __builtin_amdgcn_s_sleep(1); \
;     if ((++_sp & 255u) == 0u) { if (xb_ld(&(bar)[XB_TMO])) break; if (_sp > XB_SPIN_CAP) { atomicAdd(&(bar)[XB_TMO], 1u); break; } } } } while (0)
; __device__ __forceinline__ void xcd_barrier(const XcdBarrier& b) {
;     ...
;         if (old + 1u == (gen + 1u) * nloc) {
;             __builtin_amdgcn_fence(__ATOMIC_RELEASE, "agent");
;             asm volatile("s_waitcnt vmcnt(0)" ::: "memory");
;             const unsigned og = xb_add(&bar[XB_TOP], 1u);
;             const unsigned tg = og / nx;
;             if (og + 1u == (tg + 1u) * nx) xb_add(&bar[XB_TOPGEN], 1u);
;             else XB_SPIN(xb_ld(&bar[XB_TOPGEN]) == tg, bar);
;             __builtin_amdgcn_fence(__ATOMIC_ACQUIRE, "agent");
;             asm volatile("s_waitcnt vmcnt(0)" ::: "memory");
;         } else {
;             XB_SPIN(xb_ld(&bar[XB_TOPGEN]) == gen, bar);
;             __builtin_amdgcn_fence(__ATOMIC_ACQUIRE, "agent");
;             asm volatile("s_waitcnt vmcnt(0)" ::: "memory");
.Lxb_p0_poll:
	s_mov_b32 s100, 0
.Lxb_p0_spin:
	global_load_dword v6, v7, s[98:99] sc1
	s_waitcnt vmcnt(0)
	v_cmp_ge_u32_e32 vcc, v6, v5
	s_cbranch_vccnz .Lxb_p0_done
	s_sleep 1
	s_add_i32 s100, s100, 1
	s_cmp_lt_u32 s100, 0x40000
	s_cbranch_scc1 .Lxb_p0_spin
.Lxb_p0_done:
.LBB0_125:
	s_or_b64 exec, exec, s[0:1]
	s_waitcnt lgkmcnt(0)
	s_barrier

; __device__ __forceinline__ unsigned xb_ld(unsigned* p)              { return __hip_atomic_load(p, __ATOMIC_RELAXED, __HIP_MEMORY_SCOPE_AGENT); }
; __device__ __forceinline__ unsigned xb_add(unsigned* p, unsigned v) { return __hip_atomic_fetch_add(p, v, __ATOMIC_RELAXED, __HIP_MEMORY_SCOPE_AGENT); }
; #define XB_SPIN(cond, bar) do { unsigned _sp = 0; while (cond) { __builtin_amdgcn_s_sleep(1); \
;     if ((++_sp & 255u) == 0u) { if (xb_ld(&(bar)[XB_TMO])) break; if (_sp > XB_SPIN_CAP) { atomicAdd(&(bar)[XB_TMO], 1u); break; } } } } while (0)
; __device__ __forceinline__ void xcd_barrier(const XcdBarrier& b) {
;     ...
;         unsigned nloc = b.st[0], nx = b.st[1];
;         if (nloc == 0u) { xcd_barrier_complete(bar, b.x, nloc, nx); b.st[0] = nloc; b.st[1] = nx; }
;         const unsigned old = xb_add(&bar[XB_XSUB(b.x)], 1u);
;         const unsigned gen = old / nloc;
;         if (old + 1u == (gen + 1u) * nloc) {
;             __builtin_amdgcn_fence(__ATOMIC_RELEASE, "agent");
;             asm volatile("s_waitcnt vmcnt(0)" ::: "memory");
;             const unsigned og = xb_add(&bar[XB_TOP], 1u);
;             const unsigned tg = og / nx;
;             if (og + 1u == (tg + 1u) * nx) xb_add(&bar[XB_TOPGEN], 1u);
;             else XB_SPIN(xb_ld(&bar[XB_TOPGEN]) == tg, bar);
;             __builtin_amdgcn_fence(__ATOMIC_ACQUIRE, "agent");
;             asm volatile("s_waitcnt vmcnt(0)" ::: "memory");
;         } else {
;             XB_SPIN(xb_ld(&bar[XB_TOPGEN]) == gen, bar);
.LBB0_333:
	v_readlane_b32 s4, v253, 35
	v_readlane_b32 s5, v253, 36
	v_cvt_f32_u32_e32 v1, v2
	v_sub_u32_e32 v4, 0, v2
	v_rcp_iflag_f32_e32 v1, v1
	s_nop 1
	global_atomic_add v3, v177, v238, s[4:5] sc0
	v_mul_f32_e32 v1, 0x4f7ffffe, v1
	v_cvt_u32_f32_e32 v1, v1
	v_mul_lo_u32 v4, v4, v1
	v_mul_hi_u32 v4, v1, v4
	v_add_u32_e32 v1, v1, v4
	s_waitcnt vmcnt(0)
	v_mul_hi_u32 v1, v3, v1
	v_mul_lo_u32 v4, v1, v2
	v_sub_u32_e32 v4, v3, v4
	v_add_u32_e32 v5, 1, v1
	v_cmp_ge_u32_e32 vcc, v4, v2
	v_add_u32_e32 v3, 1, v3
	s_nop 0
	v_cndmask_b32_e32 v1, v1, v5, vcc
	v_sub_u32_e32 v5, v4, v2
	v_cndmask_b32_e32 v4, v4, v5, vcc
	v_add_u32_e32 v5, 1, v1
	v_cmp_ge_u32_e32 vcc, v4, v2
	s_nop 1
	v_cndmask_b32_e32 v1, v1, v5, vcc
	v_mul_lo_u32 v4, v2, v1
	v_add_u32_e32 v2, v4, v2
	v_cmp_ne_u32_e32 vcc, v3, v2
	s_waitcnt lgkmcnt(0)
	v_add_u32_e32 v4, 1, v1
	v_mul_lo_u32 v4, v4, v0
	v_readlane_b32 s98, v253, 39
	v_readlane_b32 s99, v253, 40
	s_nop 4
	s_cbranch_vccnz .Lxb_b1_nl
	buffer_wbl2 sc1
	s_waitcnt vmcnt(0)
	global_atomic_add v177, v238, s[98:99]
	buffer_inv sc1
	s_branch .Lxb_b1_poll

; __device__ __forceinline__ unsigned xb_ld(unsigned* p)              { return __hip_atomic_load(p, __ATOMIC_RELAXED, __HIP_MEMORY_SCOPE_AGENT); }
; #define XB_SPIN(cond, bar) do { unsigned _sp = 0; while (cond) { __builtin_amdgcn_s_sleep(1); \
;     if ((++_sp & 255u) == 0u) { if (xb_ld(&(bar)[XB_TMO])) break; if (_sp > XB_SPIN_CAP) { atomicAdd(&(bar)[XB_TMO], 1u); break; } } } } while (0)
; __device__ __forceinline__ void xcd_barrier(const XcdBarrier& b) {
;     ...
;             else XB_SPIN(xb_ld(&bar[XB_TOPGEN]) == tg, bar);
;             __builtin_amdgcn_fence(__ATOMIC_ACQUIRE, "agent");
;             asm volatile("s_waitcnt vmcnt(0)" ::: "memory");
;         } else {
;             XB_SPIN(xb_ld(&bar[XB_TOPGEN]) == gen, bar);
.Lxb_b1_spin:
	global_load_dword v5, v177, s[98:99] sc1
	s_waitcnt vmcnt(0)
	v_cmp_ge_u32_e32 vcc, v5, v4
	s_cbranch_vccnz .Lxb_b1_done
	s_sleep 1
	s_add_i32 s100, s100, 1
	s_cmp_lt_u32 s100, 0x40000
	s_cbranch_scc1 .Lxb_b1_spin

; __device__ __forceinline__ unsigned xb_ld(unsigned* p)              { return __hip_atomic_load(p, __ATOMIC_RELAXED, __HIP_MEMORY_SCOPE_AGENT); }
; #define XB_SPIN(cond, bar) do { unsigned _sp = 0; while (cond) { __builtin_amdgcn_s_sleep(1); \
;     if ((++_sp & 255u) == 0u) { if (xb_ld(&(bar)[XB_TMO])) break; if (_sp > XB_SPIN_CAP) { atomicAdd(&(bar)[XB_TMO], 1u); break; } } } } while (0)
; __device__ __forceinline__ void xcd_barrier(const XcdBarrier& b) {
;     ...
;             else XB_SPIN(xb_ld(&bar[XB_TOPGEN]) == tg, bar);
;             __builtin_amdgcn_fence(__ATOMIC_ACQUIRE, "agent");
;             asm volatile("s_waitcnt vmcnt(0)" ::: "memory");
;         } else {
;             XB_SPIN(xb_ld(&bar[XB_TOPGEN]) == gen, bar);
;             __builtin_amdgcn_fence(__ATOMIC_ACQUIRE, "agent");
;             asm volatile("s_waitcnt vmcnt(0)" ::: "memory");
;         }
;     }
;     __syncthreads();
.Lxb_b5_done:
	s_branch .LBB0_128
